# ResNorm epilogue: residual-stream f32 stores transposed through the per-wave LDS ring so each store instruction writes whole 128-byte lines; issued before the norm/adaLN vector loads
# speedup vs baseline: 1.0324x; 1.0049x over previous
.LBB0_917:
	s_or_b64 exec, exec, s[36:37]
	s_and_b64 vcc, exec, s[38:39]
	s_cbranch_vccnz .Lxs_skip
	s_lshl_b32 s98, s22, 20
	s_lshr_b32 s99, s22, 12
	s_add_u32 s98, s98, s76
	s_addc_u32 s99, s99, s77
	s_mul_i32 s100, s33, 192
	s_add_i32 s100, s100, 0x4000
	v_and_b32_e32 v247, 15, v219
	v_lshrrev_b32_e32 v193, 4, v219
	v_and_b32_e32 v244, 7, v247
	v_xor_b32_e32 v193, v193, v244
	v_lshlrev_b32_e32 v244, 7, v247
	v_add_u32_e32 v244, s100, v244
	v_xor_b32_e32 v245, 4, v193
	v_lshl_add_u32 v245, v245, 4, v244
	v_lshl_add_u32 v244, v193, 4, v244
	v_lshlrev_b32_e32 v246, 4, v219
	v_add_u32_e32 v246, s100, v246
	ds_write_b128 v244, v[156:159] offset:0
	ds_write_b128 v245, v[152:155] offset:0
	ds_write_b128 v244, v[148:151] offset:2048
	ds_write_b128 v245, v[116:119] offset:2048
	s_waitcnt lgkmcnt(0)
	ds_read_b128 v[226:229], v246 offset:0
	ds_read_b128 v[230:233], v246 offset:1024
	ds_read_b128 v[234:237], v246 offset:2048
	ds_read_b128 v[238:241], v246 offset:3072
	s_add_u32 s100, s98, 0x0
	s_addc_u32 s101, s99, 0
	s_waitcnt lgkmcnt(3)
	global_store_dwordx4 v212, v[226:229], s[100:101]
	s_add_u32 s100, s98, 0x8000
	s_addc_u32 s101, s99, 0
	s_waitcnt lgkmcnt(2)
	global_store_dwordx4 v212, v[230:233], s[100:101]
	s_add_u32 s100, s98, 0x200
	s_addc_u32 s101, s99, 0
	s_waitcnt lgkmcnt(1)
	global_store_dwordx4 v212, v[234:237], s[100:101]
	s_add_u32 s100, s98, 0x8200
	s_addc_u32 s101, s99, 0
	s_waitcnt lgkmcnt(0)
	global_store_dwordx4 v212, v[238:241], s[100:101]
	ds_write_b128 v244, v[144:147] offset:4096
	ds_write_b128 v245, v[124:127] offset:4096
	ds_write_b128 v244, v[104:107] offset:6144
	ds_write_b128 v245, v[92:95] offset:6144
	s_waitcnt lgkmcnt(0)
	ds_read_b128 v[226:229], v246 offset:4096
	ds_read_b128 v[230:233], v246 offset:5120
	ds_read_b128 v[234:237], v246 offset:6144
	ds_read_b128 v[238:241], v246 offset:7168
	s_add_u32 s100, s98, 0x10000
	s_addc_u32 s101, s99, 0
	s_waitcnt lgkmcnt(3)
	global_store_dwordx4 v212, v[226:229], s[100:101]
	s_add_u32 s100, s98, 0x18000
	s_addc_u32 s101, s99, 0
	s_waitcnt lgkmcnt(2)
	global_store_dwordx4 v212, v[230:233], s[100:101]
	s_add_u32 s100, s98, 0x10200
	s_addc_u32 s101, s99, 0
	s_waitcnt lgkmcnt(1)
	global_store_dwordx4 v212, v[234:237], s[100:101]
	s_add_u32 s100, s98, 0x18200
	s_addc_u32 s101, s99, 0
	s_waitcnt lgkmcnt(0)
	global_store_dwordx4 v212, v[238:241], s[100:101]
	ds_write_b128 v244, v[96:99] offset:8192
	ds_write_b128 v245, v[88:91] offset:8192
	ds_write_b128 v244, v[84:87] offset:10240
	ds_write_b128 v245, v[76:79] offset:10240
	s_waitcnt lgkmcnt(0)
	ds_read_b128 v[226:229], v246 offset:8192
	ds_read_b128 v[230:233], v246 offset:9216
	ds_read_b128 v[234:237], v246 offset:10240
	ds_read_b128 v[238:241], v246 offset:11264
	s_add_u32 s100, s98, 0x20000
	s_addc_u32 s101, s99, 0
	s_waitcnt lgkmcnt(3)
	global_store_dwordx4 v212, v[226:229], s[100:101]
	s_add_u32 s100, s98, 0x28000
	s_addc_u32 s101, s99, 0
	s_waitcnt lgkmcnt(2)
	global_store_dwordx4 v212, v[230:233], s[100:101]
	s_add_u32 s100, s98, 0x20200
	s_addc_u32 s101, s99, 0
	s_waitcnt lgkmcnt(1)
	global_store_dwordx4 v212, v[234:237], s[100:101]
	s_add_u32 s100, s98, 0x28200
	s_addc_u32 s101, s99, 0
	s_waitcnt lgkmcnt(0)
	global_store_dwordx4 v212, v[238:241], s[100:101]
	ds_write_b128 v244, v[80:83] offset:0
	ds_write_b128 v245, v[72:75] offset:0
	ds_write_b128 v244, v[68:71] offset:2048
	ds_write_b128 v245, v[60:63] offset:2048
	s_waitcnt lgkmcnt(0)
	ds_read_b128 v[226:229], v246 offset:0
	ds_read_b128 v[230:233], v246 offset:1024
	ds_read_b128 v[234:237], v246 offset:2048
	ds_read_b128 v[238:241], v246 offset:3072
	s_add_u32 s100, s98, 0x30000
	s_addc_u32 s101, s99, 0
	s_waitcnt lgkmcnt(3)
	global_store_dwordx4 v212, v[226:229], s[100:101]
	s_add_u32 s100, s98, 0x38000
	s_addc_u32 s101, s99, 0
	s_waitcnt lgkmcnt(2)
	global_store_dwordx4 v212, v[230:233], s[100:101]
	s_add_u32 s100, s98, 0x30200
	s_addc_u32 s101, s99, 0
	s_waitcnt lgkmcnt(1)
	global_store_dwordx4 v212, v[234:237], s[100:101]
	s_add_u32 s100, s98, 0x38200
	s_addc_u32 s101, s99, 0
	s_waitcnt lgkmcnt(0)
	global_store_dwordx4 v212, v[238:241], s[100:101]
	ds_write_b128 v244, v[64:67] offset:4096
	ds_write_b128 v245, v[56:59] offset:4096
	ds_write_b128 v244, v[52:55] offset:6144
	ds_write_b128 v245, v[44:47] offset:6144
	s_waitcnt lgkmcnt(0)
	ds_read_b128 v[226:229], v246 offset:4096
	ds_read_b128 v[230:233], v246 offset:5120
	ds_read_b128 v[234:237], v246 offset:6144
	ds_read_b128 v[238:241], v246 offset:7168
	s_add_u32 s100, s98, 0x80000
	s_addc_u32 s101, s99, 0
	s_waitcnt lgkmcnt(3)
	global_store_dwordx4 v212, v[226:229], s[100:101]
	s_add_u32 s100, s98, 0x88000
	s_addc_u32 s101, s99, 0
	s_waitcnt lgkmcnt(2)
	global_store_dwordx4 v212, v[230:233], s[100:101]
	s_add_u32 s100, s98, 0x80200
	s_addc_u32 s101, s99, 0
	s_waitcnt lgkmcnt(1)
	global_store_dwordx4 v212, v[234:237], s[100:101]
	s_add_u32 s100, s98, 0x88200
	s_addc_u32 s101, s99, 0
	s_waitcnt lgkmcnt(0)
	global_store_dwordx4 v212, v[238:241], s[100:101]
	ds_write_b128 v244, v[48:51] offset:8192
	ds_write_b128 v245, v[40:43] offset:8192
	ds_write_b128 v244, v[36:39] offset:10240
	ds_write_b128 v245, v[32:35] offset:10240
	s_waitcnt lgkmcnt(0)
	ds_read_b128 v[226:229], v246 offset:8192
	ds_read_b128 v[230:233], v246 offset:9216
	ds_read_b128 v[234:237], v246 offset:10240
	ds_read_b128 v[238:241], v246 offset:11264
	s_add_u32 s100, s98, 0x90000
	s_addc_u32 s101, s99, 0
	s_waitcnt lgkmcnt(3)
	global_store_dwordx4 v212, v[226:229], s[100:101]
	s_add_u32 s100, s98, 0x98000
	s_addc_u32 s101, s99, 0
	s_waitcnt lgkmcnt(2)
	global_store_dwordx4 v212, v[230:233], s[100:101]
	s_add_u32 s100, s98, 0x90200
	s_addc_u32 s101, s99, 0
	s_waitcnt lgkmcnt(1)
	global_store_dwordx4 v212, v[234:237], s[100:101]
	s_add_u32 s100, s98, 0x98200
	s_addc_u32 s101, s99, 0
	s_waitcnt lgkmcnt(0)
	global_store_dwordx4 v212, v[238:241], s[100:101]
	ds_write_b128 v244, v[28:31] offset:0
	ds_write_b128 v245, v[24:27] offset:0
	ds_write_b128 v244, v[20:23] offset:2048
	ds_write_b128 v245, v[16:19] offset:2048
	s_waitcnt lgkmcnt(0)
	ds_read_b128 v[226:229], v246 offset:0
	ds_read_b128 v[230:233], v246 offset:1024
	ds_read_b128 v[234:237], v246 offset:2048
	ds_read_b128 v[238:241], v246 offset:3072
	s_add_u32 s100, s98, 0xa0000
	s_addc_u32 s101, s99, 0
	s_waitcnt lgkmcnt(3)
	global_store_dwordx4 v212, v[226:229], s[100:101]
	s_add_u32 s100, s98, 0xa8000
	s_addc_u32 s101, s99, 0
	s_waitcnt lgkmcnt(2)
	global_store_dwordx4 v212, v[230:233], s[100:101]
	s_add_u32 s100, s98, 0xa0200
	s_addc_u32 s101, s99, 0
	s_waitcnt lgkmcnt(1)
	global_store_dwordx4 v212, v[234:237], s[100:101]
	s_add_u32 s100, s98, 0xa8200
	s_addc_u32 s101, s99, 0
	s_waitcnt lgkmcnt(0)
	global_store_dwordx4 v212, v[238:241], s[100:101]
	ds_write_b128 v244, v[12:15] offset:4096
	ds_write_b128 v245, v[8:11] offset:4096
	ds_write_b128 v244, v[4:7] offset:6144
	ds_write_b128 v245, v[0:3] offset:6144
	s_waitcnt lgkmcnt(0)
	ds_read_b128 v[226:229], v246 offset:4096
	ds_read_b128 v[230:233], v246 offset:5120
	ds_read_b128 v[234:237], v246 offset:6144
	ds_read_b128 v[238:241], v246 offset:7168
	s_add_u32 s100, s98, 0xb0000
	s_addc_u32 s101, s99, 0
	s_waitcnt lgkmcnt(3)
	global_store_dwordx4 v212, v[226:229], s[100:101]
	s_add_u32 s100, s98, 0xb8000
	s_addc_u32 s101, s99, 0
	s_waitcnt lgkmcnt(2)
	global_store_dwordx4 v212, v[230:233], s[100:101]
	s_add_u32 s100, s98, 0xb0200
	s_addc_u32 s101, s99, 0
	s_waitcnt lgkmcnt(1)
	global_store_dwordx4 v212, v[234:237], s[100:101]
	s_add_u32 s100, s98, 0xb8200
	s_addc_u32 s101, s99, 0
	s_waitcnt lgkmcnt(0)
	global_store_dwordx4 v212, v[238:241], s[100:101]
.Lxs_skip:
	v_lshlrev_b32_e32 v193, 2, v210
	global_load_dwordx4 v[128:131], v193, s[58:59]
	global_load_dwordx4 v[136:139], v193, s[58:59] offset:64
	global_load_dwordx4 v[120:123], v193, s[58:59] offset:512
	global_load_dwordx4 v[112:115], v193, s[58:59] offset:576
	s_and_b64 vcc, exec, s[38:39]
	s_cbranch_vccnz .Lmh_nomod_a
	v_readlane_b32 s98, v255, 14
	v_readlane_b32 s99, v255, 15
	s_add_u32 s100, s44, s2
	s_addc_u32 s101, s45, s3
	s_add_u32 s98, s98, s2
	s_addc_u32 s99, s99, s3
	global_load_dwordx4 v[140:143], v193, s[100:101]
	global_load_dwordx4 v[108:111], v193, s[100:101] offset:64
	global_load_dwordx4 v[132:135], v193, s[100:101] offset:512
	global_load_dwordx4 v[100:103], v193, s[100:101] offset:576
	global_load_dwordx4 v[226:229], v193, s[98:99]
	global_load_dwordx4 v[230:233], v193, s[98:99] offset:64
	global_load_dwordx4 v[234:237], v193, s[98:99] offset:512
	global_load_dwordx4 v[238:241], v193, s[98:99] offset:576
